# flips deleted plus ONE static s_setprio 1 for waves 0-3 at kernel entry (other half)
# baseline (speedup 1.0000x reference)
; __device__ __forceinline__ int lane_fresh() { int l; asm volatile("v_mbcnt_lo_u32_b32 %0, -1, 0\n\tv_mbcnt_hi_u32_b32 %0, -1, %0" : "=v"(l)); return l; }
; __device__ __forceinline__ unsigned xb_add(unsigned* p, unsigned v) { return __hip_atomic_fetch_add(p, v, __ATOMIC_RELAXED, __HIP_MEMORY_SCOPE_AGENT); }
; __device__ __forceinline__ unsigned xb_xcc_id() { return (unsigned)__builtin_amdgcn_s_getreg((3 << 11) | 20) & 0xFu; }
; __global__ void __launch_bounds__(NTHREADS) fwd_megakernel(Params p) {
;   cg::grid_group grid = cg::this_grid();
;   const int wv = __builtin_amdgcn_readfirstlane(threadIdx.x >> 6);
;     ...
;   unsigned* bar = (unsigned*)(p.ws + OFF_BAR);
;   if (wv == 0) { if (lane_fresh() == 0) { xb_words = make_uint4(0u, 0u, 0u, 0u); (void)xb_add(&bar[XB_XCNT(xb_xcc_id())], 1u); } }
_Z14fwd_megakernel6Params:
	v_readfirstlane_b32 s100, v0
	s_nop 3
	s_bfe_u32 s100, s100, 0x40006
	s_cmp_ge_u32 s100, 4
	s_cbranch_scc1 .Lprio_k
	s_setprio 1
